# sample-row activations (h2 and relu2 T of the 128 decode rows) stored tile-major so the small-GEMM A fragments are contiguous 1 KiB reads instead of 16 strided half lines
# speedup vs baseline: 1.0680x; 1.0156x over previous
; __device__ __forceinline__ int fresh_tid() { int t = threadIdx.x; asm volatile("" : "+v"(t)); return t; }
;     const int tid = fresh_tid(), lane = tid & 63, gw = blockIdx.x * 8 + (tid >> 6), nw = (nblk ? nblk : (int)gridDim.x) * 8;
;     const float* mod = (const float*)(p.ws + WS_MOD); bf16_t* H = (bf16_t*)(p.ws + WS_H);
;     f32x4 gv[4];
; #pragma unroll
;     for (int i = 0; i < 4; ++i) gv[i] = *(const f32x4*)(g + (i >> 1) * 512 + lane * 8 + (i & 1) * 4);
;     for (int rowb = r0 + gw; rowb < r1; rowb += 4 * nw) {
;         f32x4 v[4][4];
; #pragma unroll
;         for (int q = 0; q < 4; ++q) { const int row = rowb + q * nw;
;             if (row < r1) { const float* src = from_out ? p.out + (size_t)row * DM : (row < NP ? p.x_prompt + (size_t)row * DM : p.x_sample + (size_t)(row - NP) * DM);
; #pragma unroll
;                 for (int i = 0; i < 4; ++i) v[q][i] = *(const f32x4*)(src + (i >> 1) * 512 + lane * 8 + (i & 1) * 4); }
; __global__ __launch_bounds__(512, 2) void fwd_megakernel(Params p) {
;     ...
;       if (bid < 16) {
;           rownorm_phase<false, true>(p, p.g_ffn, 3072, 4096, true, NP, NTOK, 16);
.LBB0_633:
	s_or_b64 exec, exec, s[0:1]
	s_add_u32 s24, s58, 0xc944000
	s_addc_u32 s25, s59, 0
	s_cmp_lt_i32 s2, 16
	s_cselect_b64 s[20:21], -1, 0
	s_and_b64 vcc, exec, s[20:21]
	s_waitcnt lgkmcnt(0)
	s_barrier
	s_cbranch_vccz .LBB0_653
	v_mov_b32_e32 v17, v224
	s_movk_i32 s0, 0x4080
	v_ashrrev_i32_e32 v18, 6, v17
	v_add_u32_e32 v16, s97, v18
	v_cmp_gt_i32_e32 vcc, s0, v16
	s_and_saveexec_b64 s[36:37], vcc
	s_cbranch_execz .LBB0_649
	v_lshlrev_b32_e32 v0, 3, v17
	v_and_b32_e32 v64, 0x1f8, v0
	v_lshlrev_b32_e32 v19, 2, v64
	global_load_dwordx4 v[0:3], v19, s[28:29] offset:16
	global_load_dwordx4 v[4:7], v19, s[28:29]
	global_load_dwordx4 v[8:11], v19, s[28:29] offset:2064
	global_load_dwordx4 v[12:15], v19, s[28:29] offset:2048
	v_and_b32_e32 v17, 63, v17
	v_lshlrev_b32_e32 v68, 5, v17
	v_ashrrev_i32_e32 v17, 31, v16
	v_add_u32_e32 v21, s95, v18
	v_lshlrev_b64 v[18:19], 12, v[16:17]
	v_lshl_add_u64 v[70:71], s[56:57], 0, v[18:19]
	v_add_u32_e32 v18, 0x4180, v21
	s_mov_b64 s[0:1], 0x1a70000
	v_lshlrev_b64 v[16:17], 11, v[16:17]
	v_ashrrev_i32_e32 v19, 31, v18
	v_and_b32_e32 v76, 15, v21
	v_lshlrev_b32_e32 v76, 4, v76
	v_and_b32_e32 v77, -16, v21
	v_lshl_add_u32 v76, v77, 11, v76
	v_mul_u32_u24_e32 v77, 30, v64
	v_add_u32_e32 v76, v76, v77
	v_add_u32_e32 v76, 0x3a70000, v76
	v_mov_b32_e32 v77, 0
	v_add_u32_e32 v16, 0x4100, v21
	v_lshlrev_b64 v[22:23], 12, v[18:19]
	v_lshlrev_b64 v[18:19], 11, v[18:19]
	v_ashrrev_i32_e32 v17, 31, v16
	v_lshl_add_u64 v[74:75], v[18:19], 0, s[0:1]
	v_lshlrev_b64 v[18:19], 12, v[16:17]
	v_lshlrev_b64 v[16:17], 11, v[16:17]
	v_lshl_add_u64 v[80:81], v[16:17], 0, s[0:1]
	v_add_u32_e32 v16, 0x4080, v21
	v_ashrrev_i32_e32 v17, 31, v16
	v_mov_b32_e32 v67, 0
	v_or_b32_e32 v20, 0x200, v64
	v_lshl_add_u64 v[78:79], s[56:57], 0, v[18:19]
	v_lshlrev_b64 v[18:19], 12, v[16:17]
	v_lshlrev_b64 v[16:17], 11, v[16:17]
	v_add_u32_e32 v89, 0x3e00, v21
	v_mov_b32_e32 v69, v67
	v_lshl_add_u64 v[72:73], s[56:57], 0, v[22:23]
	v_lshl_add_u64 v[82:83], s[56:57], 0, v[18:19]
	v_lshl_add_u64 v[84:85], v[16:17], 0, s[0:1]
	s_mov_b64 s[28:29], 0
	s_movk_i32 s12, 0x4000
	s_movk_i32 s13, 0x3f80
	s_movk_i32 s33, 0x3f00
	s_mov_b32 s38, 0x3a800000
	s_mov_b32 s39, 0x800000
	s_movk_i32 s60, 0x6000
	s_mov_b64 s[44:45], 0x4000
	s_mov_b64 s[46:47], 0x3000
	s_mov_b64 s[48:49], 0x400
	v_lshlrev_b32_e32 v86, 2, v20
	v_mov_b32_e32 v88, 0x358637bd
	s_movk_i32 s61, 0x3e80
	s_mov_b64 s[50:51], 0x200000
	s_movk_i32 s64, 0x3e7f
	s_mov_b64 s[52:53], s[58:59]
	s_branch .LBB0_637

;     ...
;         for (int q = 0; q < 4; ++q) { float ss = 0.f;
; #pragma unroll
;             for (int i = 0; i < 4; ++i) ss += v[q][i][0] * v[q][i][0] + v[q][i][1] * v[q][i][1] + v[q][i][2] * v[q][i][2] + v[q][i][3] * v[q][i][3];
; #pragma unroll
;             for (int o = 1; o < 64; o <<= 1) ss += __shfl_xor(ss, o);
;             rs[q] = rsqrtf(ss * (1.f / DM) + EPS); }
; #pragma unroll
;         for (int q = 0; q < 4; ++q) { const int row = rowb + q * nw;
;             if (row < r1) { const float* mb = mod + (size_t)batch_of(row) * NMOD;
; #pragma unroll
;                 for (int h = 0; h < 2; ++h) { const int c = h * 512 + lane * 8;
;                     const f32x4 y0 = v[q][2 * h] * rs[q] * gv[2 * h], y1 = v[q][2 * h + 1] * rs[q] * gv[2 * h + 1];
;                     if (FINAL) { *(f32x4*)(p.out + (size_t)row * DM + c) = y0; *(f32x4*)(p.out + (size_t)row * DM + c + 4) = y1; }
;                     else { if (WT) st_wt_bf16x8(H + (size_t)row * DM + c, y0 * (*(const f32x4*)(mb + sc_off + c) + 1.f) + *(const f32x4*)(mb + sh_off + c),
.LBB0_643:
	s_or_b64 exec, exec, s[0:1]
	s_waitcnt vmcnt(2)
	v_mov_b32_e32 v108, v61
	v_mov_b32_e32 v109, v57
	v_mov_b32_e32 v106, v60
	v_mov_b32_e32 v107, v56
	v_pk_mul_f32 v[108:109], v[108:109], v[108:109]
	s_waitcnt vmcnt(0)
	v_mov_b32_e32 v110, v53
	v_pk_fma_f32 v[106:107], v[106:107], v[106:107], v[108:109]
	v_mov_b32_e32 v108, v62
	v_mov_b32_e32 v109, v58
	v_pk_fma_f32 v[106:107], v[108:109], v[108:109], v[106:107]
	v_mov_b32_e32 v108, v63
	v_mov_b32_e32 v109, v59
	v_mov_b32_e32 v111, v49
	v_pk_fma_f32 v[108:109], v[108:109], v[108:109], v[106:107]
	v_mov_b32_e32 v106, v52
	v_mov_b32_e32 v107, v48
	v_pk_mul_f32 v[110:111], v[110:111], v[110:111]
	v_ashrrev_i32_e32 v66, 11, v65
	v_pk_fma_f32 v[106:107], v[106:107], v[106:107], v[110:111]
	v_mov_b32_e32 v110, v54
	v_mov_b32_e32 v111, v50
	v_pk_fma_f32 v[106:107], v[110:111], v[110:111], v[106:107]
	v_mov_b32_e32 v110, v55
	v_mov_b32_e32 v111, v51
	v_pk_fma_f32 v[126:127], v[110:111], v[110:111], v[106:107]
	v_pk_mul_f32 v[106:107], v[96:97], v[96:97]
	v_add_u32_e32 v87, 0xffffc208, v89
	v_pk_fma_f32 v[106:107], v[16:17], v[16:17], v[106:107]
	v_cndmask_b32_e64 v66, v87, v66, s[6:7]
	v_pk_fma_f32 v[128:129], v[18:19], v[18:19], v[106:107]
	v_mov_b64_e32 v[106:107], s[16:17]
	v_mad_i64_i32 v[106:107], s[0:1], v66, s60, v[106:107]
	v_lshl_add_u64 v[130:131], v[106:107], 0, s[44:45]
	v_lshl_add_u64 v[132:133], v[106:107], 0, s[46:47]
	v_lshlrev_b32_e32 v106, 2, v64
	v_mov_b32_e32 v107, v67
	v_lshl_add_u64 v[114:115], v[130:131], 0, v[106:107]
	global_load_dwordx4 v[110:113], v[114:115], off offset:16
	s_nop 0
	global_load_dwordx4 v[114:117], v[114:115], off
	v_lshl_add_u64 v[122:123], v[132:133], 0, v[106:107]
	global_load_dwordx4 v[118:121], v[122:123], off offset:16
	s_nop 0
	global_load_dwordx4 v[122:125], v[122:123], off
	v_pk_mul_f32 v[134:135], v[92:93], v[92:93]
	v_pk_fma_f32 v[128:129], v[94:95], v[94:95], v[128:129]
	v_pk_fma_f32 v[134:135], v[20:21], v[20:21], v[134:135]
	v_mov_b32_e32 v136, v108
	v_pk_fma_f32 v[134:135], v[22:23], v[22:23], v[134:135]
	v_mov_b32_e32 v137, v128
	v_pk_fma_f32 v[134:135], v[90:91], v[90:91], v[134:135]
	v_mov_b32_e32 v128, v109
	v_pk_add_f32 v[108:109], v[136:137], v[128:129]
	v_mov_b32_e32 v128, v126
	v_mov_b32_e32 v129, v134
	v_pk_add_f32 v[108:109], v[108:109], v[128:129]
	v_mov_b32_e32 v134, v127
	v_pk_add_f32 v[108:109], v[108:109], v[134:135]
	ds_bpermute_b32 v126, v225, v108
	ds_bpermute_b32 v127, v225, v109
	s_waitcnt lgkmcnt(0)
	v_pk_add_f32 v[108:109], v[108:109], v[126:127]
	ds_bpermute_b32 v126, v226, v108
	ds_bpermute_b32 v127, v226, v109
	s_waitcnt lgkmcnt(0)
	v_pk_add_f32 v[108:109], v[108:109], v[126:127]
	ds_bpermute_b32 v126, v227, v108
	ds_bpermute_b32 v127, v227, v109
	s_waitcnt lgkmcnt(0)
	v_pk_add_f32 v[108:109], v[108:109], v[126:127]
	ds_bpermute_b32 v126, v228, v108
	ds_bpermute_b32 v127, v228, v109
	s_waitcnt lgkmcnt(0)
	v_pk_add_f32 v[108:109], v[108:109], v[126:127]
	ds_bpermute_b32 v126, v229, v108
	ds_bpermute_b32 v127, v229, v109
	s_waitcnt lgkmcnt(0)
	v_pk_add_f32 v[108:109], v[108:109], v[126:127]
	ds_bpermute_b32 v126, v230, v108
	ds_bpermute_b32 v127, v230, v109
	s_waitcnt lgkmcnt(0)
	v_pk_add_f32 v[108:109], v[108:109], v[126:127]
	s_nop 0
	v_pk_fma_f32 v[108:109], v[108:109], s[38:39], v[88:89] op_sel_hi:[1,0,0]
	v_lshl_add_u64 v[126:127], s[52:53], 0, v[76:77]
	v_mul_f32_e32 v66, 0x4b800000, v108
	v_cmp_gt_f32_e64 s[0:1], s39, v108
	v_cmp_gt_f32_e64 s[8:9], s39, v109
	s_waitcnt vmcnt(3)
	v_pk_add_f32 v[112:113], v[112:113], 1.0 op_sel_hi:[1,0]
	v_cndmask_b32_e64 v66, v108, v66, s[0:1]
	v_rsq_f32_e32 v66, v66
	s_waitcnt vmcnt(2)
	v_pk_add_f32 v[116:117], v[116:117], 1.0 op_sel_hi:[1,0]
	v_pk_add_f32 v[114:115], v[114:115], 1.0 op_sel_hi:[1,0]
	v_pk_add_f32 v[110:111], v[110:111], 1.0 op_sel_hi:[1,0]
	v_mul_f32_e32 v87, 0x45800000, v66
	v_cndmask_b32_e64 v108, v66, v87, s[0:1]
	v_pk_mul_f32 v[62:63], v[62:63], v[108:109] op_sel_hi:[1,0]
	v_pk_mul_f32 v[60:61], v[60:61], v[108:109] op_sel_hi:[1,0]
	v_pk_mul_f32 v[58:59], v[58:59], v[108:109] op_sel_hi:[1,0]
	v_pk_mul_f32 v[56:57], v[56:57], v[108:109] op_sel_hi:[1,0]
	v_pk_mul_f32 v[60:61], v[4:5], v[60:61]
	v_pk_mul_f32 v[62:63], v[6:7], v[62:63]
	v_pk_mul_f32 v[56:57], v[0:1], v[56:57]
	v_pk_mul_f32 v[58:59], v[2:3], v[58:59]
	v_lshlrev_b32_e32 v66, 1, v64
	s_waitcnt vmcnt(0)
; __device__ __forceinline__ void st_bf16x8(bf16_t* p, const f32x4 a, const f32x4 b) { uint4 o; o.x = cvt_pk_bf16(a[0], a[1]); o.y = cvt_pk_bf16(a[2], a[3]); o.z = cvt_pk_bf16(b[0], b[1]); o.w = cvt_pk_bf16(b[2], b[3]); *(uint4*)p = o; }
;     ...
;         for (int q = 0; q < 4; ++q) { const int row = rowb + q * nw;
;             if (row < r1) { const float* mb = mod + (size_t)batch_of(row) * NMOD;
; #pragma unroll
;                 for (int h = 0; h < 2; ++h) { const int c = h * 512 + lane * 8;
;                     const f32x4 y0 = v[q][2 * h] * rs[q] * gv[2 * h], y1 = v[q][2 * h + 1] * rs[q] * gv[2 * h + 1];
;                     if (FINAL) { *(f32x4*)(p.out + (size_t)row * DM + c) = y0; *(f32x4*)(p.out + (size_t)row * DM + c + 4) = y1; }
;                     else { if (WT) st_wt_bf16x8(H + (size_t)row * DM + c, y0 * (*(const f32x4*)(mb + sc_off + c) + 1.f) + *(const f32x4*)(mb + sh_off + c),
;                                                              y1 * (*(const f32x4*)(mb + sc_off + c + 4) + 1.f) + *(const f32x4*)(mb + sh_off + c + 4)); else st_bf16x8(H + (size_t)row * DM + c, y0 * (*(const f32x4*)(mb + sc_off + c) + 1.f) + *(const f32x4*)(mb + sh_off + c),
;                                                              y1 * (*(const f32x4*)(mb + sc_off + c + 4) + 1.f) + *(const f32x4*)(mb + sh_off + c + 4)); } } } }
	v_pk_fma_f32 v[62:63], v[62:63], v[116:117], v[124:125]
	v_pk_fma_f32 v[60:61], v[60:61], v[114:115], v[122:123]
	v_pk_fma_f32 v[112:113], v[58:59], v[112:113], v[120:121]
	v_pk_fma_f32 v[58:59], v[56:57], v[110:111], v[118:119]
	v_cvt_pk_bf16_f32 v56, v60, v61
	v_cvt_pk_bf16_f32 v57, v62, v63
	v_mov_b32_e32 v87, v67
	v_lshl_add_u64 v[126:127], v[126:127], 0, v[66:67]
	v_cvt_pk_bf16_f32 v58, v58, v59
	v_cvt_pk_bf16_f32 v59, v112, v113
	v_pk_mul_f32 v[54:55], v[54:55], v[108:109] op_sel_hi:[1,0]
	global_store_dwordx4 v[126:127], v[56:59], off sc1
	s_nop 1
	v_lshl_add_u64 v[56:57], v[130:131], 0, v[86:87]
	global_load_dwordx4 v[60:63], v[56:57], off
	v_lshl_add_u64 v[58:59], v[132:133], 0, v[86:87]
	global_load_dwordx4 v[110:113], v[58:59], off
	global_load_dwordx4 v[114:117], v[56:57], off offset:16
	global_load_dwordx4 v[118:121], v[58:59], off offset:16
	v_mul_f32_e32 v56, v45, v45
	v_mul_f32_e32 v57, v41, v41
	v_fmac_f32_e32 v56, v44, v44
	v_fmac_f32_e32 v57, v40, v40
	v_fmac_f32_e32 v56, v46, v46
	v_fmac_f32_e32 v57, v42, v42
	v_fmac_f32_e32 v56, v47, v47
	v_fmac_f32_e32 v57, v43, v43
	v_add_f32_e32 v56, v57, v56
	v_mul_f32_e32 v57, v37, v37
	v_fmac_f32_e32 v57, v36, v36
	v_fmac_f32_e32 v57, v38, v38
	v_fmac_f32_e32 v57, v39, v39
	v_add_f32_e32 v56, v57, v56
	v_mul_f32_e32 v57, v33, v33
	v_fmac_f32_e32 v57, v32, v32
	v_fmac_f32_e32 v57, v34, v34
	v_fmac_f32_e32 v57, v35, v35
	v_add_f32_e32 v122, v57, v56
	v_pk_mul_f32 v[56:57], v[104:105], v[104:105]
	v_pk_mul_f32 v[58:59], v[98:99], v[98:99]
	v_pk_fma_f32 v[56:57], v[28:29], v[28:29], v[56:57]
	v_pk_fma_f32 v[58:59], v[24:25], v[24:25], v[58:59]
	v_pk_fma_f32 v[56:57], v[30:31], v[30:31], v[56:57]
	v_pk_fma_f32 v[58:59], v[26:27], v[26:27], v[58:59]
	v_pk_fma_f32 v[56:57], v[102:103], v[102:103], v[56:57]
	v_pk_fma_f32 v[58:59], v[100:101], v[100:101], v[58:59]
	v_add_f32_e32 v56, v56, v57
	v_add_f32_e32 v56, v59, v56
	v_add_f32_e32 v56, v58, v56
	ds_bpermute_b32 v123, v225, v122
	ds_bpermute_b32 v57, v225, v56
	v_pk_mul_f32 v[52:53], v[52:53], v[108:109] op_sel_hi:[1,0]
	v_pk_mul_f32 v[54:55], v[14:15], v[54:55]
	v_pk_mul_f32 v[52:53], v[12:13], v[52:53]
	s_waitcnt lgkmcnt(1)
	v_add_f32_e32 v58, v122, v123
	s_waitcnt lgkmcnt(0)
	v_add_f32_e32 v56, v56, v57
	ds_bpermute_b32 v59, v226, v58
	ds_bpermute_b32 v57, v226, v56
	v_pk_mul_f32 v[50:51], v[50:51], v[108:109] op_sel_hi:[1,0]
	v_pk_mul_f32 v[48:49], v[48:49], v[108:109] op_sel_hi:[1,0]
	v_pk_mul_f32 v[50:51], v[10:11], v[50:51]
	s_waitcnt lgkmcnt(1)
	v_add_f32_e32 v58, v58, v59
	s_waitcnt lgkmcnt(0)
	v_add_f32_e32 v56, v56, v57
	ds_bpermute_b32 v59, v227, v58
	ds_bpermute_b32 v57, v227, v56
	v_pk_mul_f32 v[48:49], v[8:9], v[48:49]
	v_lshl_add_u64 v[122:123], v[126:127], 0, s[44:45]
	s_waitcnt lgkmcnt(1)
	v_add_f32_e32 v58, v58, v59
	s_waitcnt lgkmcnt(0)
	v_add_f32_e32 v56, v56, v57
	ds_bpermute_b32 v59, v228, v58
	ds_bpermute_b32 v57, v228, v56
	s_waitcnt lgkmcnt(1)
	v_add_f32_e32 v58, v58, v59
	s_waitcnt lgkmcnt(0)
	v_add_f32_e32 v56, v56, v57
	ds_bpermute_b32 v59, v229, v58
	ds_bpermute_b32 v57, v229, v56
	s_waitcnt lgkmcnt(1)
	v_add_f32_e32 v58, v58, v59
	s_waitcnt lgkmcnt(0)
	v_add_f32_e32 v56, v56, v57
	ds_bpermute_b32 v59, v230, v58
	ds_bpermute_b32 v57, v230, v56
	s_waitcnt vmcnt(3)
	v_pk_add_f32 v[62:63], v[62:63], 1.0 op_sel_hi:[1,0]
	v_pk_add_f32 v[60:61], v[60:61], 1.0 op_sel_hi:[1,0]
	s_waitcnt vmcnt(2)
	v_pk_fma_f32 v[54:55], v[54:55], v[62:63], v[112:113]
	v_pk_fma_f32 v[52:53], v[52:53], v[60:61], v[110:111]
	s_waitcnt vmcnt(1)
	v_pk_add_f32 v[60:61], v[116:117], 1.0 op_sel_hi:[1,0]
	v_pk_add_f32 v[62:63], v[114:115], 1.0 op_sel_hi:[1,0]
	s_waitcnt vmcnt(0)
	v_pk_fma_f32 v[60:61], v[50:51], v[60:61], v[120:121]
	v_pk_fma_f32 v[50:51], v[48:49], v[62:63], v[118:119]
	v_cvt_pk_bf16_f32 v48, v52, v53
	v_cvt_pk_bf16_f32 v49, v54, v55
	s_nop 0
	v_cvt_pk_bf16_f32 v50, v50, v51
	v_cvt_pk_bf16_f32 v51, v60, v61
	s_nop 0
	global_store_dwordx4 v[122:123], v[48:51], off sc1
	s_nop 1
	s_and_saveexec_b64 s[62:63], s[6:7]
	s_cbranch_execnz .LBB0_646
	s_or_b64 exec, exec, s[62:63]
	s_and_saveexec_b64 s[6:7], s[4:5]
	s_cbranch_execnz .LBB0_647

; template <int KSPLIT, int BATCH, bool SHAREB = false, class Epi>
; __device__ __forceinline__ void small_gemm_w(const bf16_t* __restrict__ A, int nm16, const bf16_t* __restrict__ Bt, int N, int K, const Epi& E, int row_base, float* smem) {
;     ...
;         if (KSPLIT == 1 && SHAREB) {
;             __syncthreads();
;             uint4* Bs = (uint4*)smem; const int nst = kw / 32, per = nst / 8;
;             const bf16_t* bpb = Bt + (size_t)((base / nm16) * 16 + fr) * K + fq * 8;
;             for (int j = 0; j < per; ++j) { const int s = w * per + j; Bs[s * 64 + lane] = *(const uint4*)(bpb + s * 32); }
;             __syncthreads();
;             if (valid) {
;                 const bf16_t* ap = A + (size_t)(m16 * 16 + fr) * K + fq * 8;
;                 for (int s0 = 0; s0 < nst; s0 += BATCH) { Frag a[BATCH];
; #pragma unroll
;                     for (int i = 0; i < BATCH; ++i) a[i].q = *(const uint4*)(ap + (s0 + i) * 32);
;                     __builtin_amdgcn_sched_barrier(0);
; #pragma unroll
;                     for (int i = 0; i < BATCH; ++i) { Frag b; b.q = Bs[(s0 + i) * 64 + lane]; acc = __builtin_amdgcn_mfma_f32_16x16x32_bf16(b.v, a[i].v, acc, 0, 0, 0); }
;                     __builtin_amdgcn_sched_barrier(0); } }
.LBB0_691:
	v_ashrrev_i32_e32 v19, 31, v18
	v_lshlrev_b64 v[0:1], 11, v[18:19]
	v_lshl_add_u64 v[0:1], v[6:7], 0, v[0:1]
	v_lshl_add_u64 v[2:3], v[10:11], 1, v[0:1]
	s_barrier
	v_lshl_add_u64 v[38:39], v[12:13], 1, v[0:1]
	global_load_dwordx4 v[30:33], v[2:3], off
	global_load_dwordx4 v[34:37], v[38:39], off
	v_lshl_add_u64 v[2:3], v[14:15], 1, v[0:1]
	v_lshl_add_u64 v[0:1], v[16:17], 1, v[0:1]
	global_load_dwordx4 v[38:41], v[2:3], off
	global_load_dwordx4 v[42:45], v[0:1], off
	v_add_u32_e32 v3, s8, v20
	v_ashrrev_i32_e32 v4, 31, v3
	v_lshrrev_b32_e32 v4, 29, v4
	v_add_u32_e32 v19, v3, v4
	v_and_b32_e32 v4, -8, v19
	v_mov_b32_e32 v0, 0
	v_mov_b32_e32 v1, 0
	v_mov_b32_e32 v2, 0
	v_cmp_gt_i32_e32 vcc, s7, v3
	v_sub_u32_e32 v4, v3, v4
	v_mov_b32_e32 v3, 0
	s_waitcnt vmcnt(3)
	ds_write_b128 v24, v[30:33]
	s_waitcnt vmcnt(2)
	ds_write_b128 v25, v[34:37]
	s_waitcnt vmcnt(1)
	ds_write_b128 v26, v[38:41]
	s_waitcnt vmcnt(0)
	ds_write_b128 v27, v[42:45]
	s_waitcnt lgkmcnt(0)
	s_barrier
	s_and_saveexec_b64 s[0:1], vcc
	s_cbranch_execz .LBB0_693
	v_lshl_add_u32 v98, v4, 15, v23
	s_sub_u32 s76, s14, 16
	s_subb_u32 s77, s15, 0
	global_load_dwordx4 v[0:3], v98, s[76:77]
	global_load_dwordx4 v[30:33], v98, s[76:77] offset:1024
	global_load_dwordx4 v[34:37], v98, s[76:77] offset:2048
	global_load_dwordx4 v[38:41], v98, s[76:77] offset:3072
	s_add_u32 s76, s76, 0x1000
	s_addc_u32 s77, s77, 0
	global_load_dwordx4 v[42:45], v98, s[76:77]
	global_load_dwordx4 v[46:49], v98, s[76:77] offset:1024
	global_load_dwordx4 v[50:53], v98, s[76:77] offset:2048
	global_load_dwordx4 v[54:57], v98, s[76:77] offset:3072
	s_add_u32 s76, s76, 0x1000
	s_addc_u32 s77, s77, 0
	global_load_dwordx4 v[58:61], v98, s[76:77]
	global_load_dwordx4 v[62:65], v98, s[76:77] offset:1024
	global_load_dwordx4 v[66:69], v98, s[76:77] offset:2048
	global_load_dwordx4 v[70:73], v98, s[76:77] offset:3072
	s_add_u32 s76, s76, 0x1000
	s_addc_u32 s77, s77, 0
	global_load_dwordx4 v[74:77], v98, s[76:77]
	global_load_dwordx4 v[78:81], v98, s[76:77] offset:1024
	global_load_dwordx4 v[82:85], v98, s[76:77] offset:2048
	global_load_dwordx4 v[86:89], v98, s[76:77] offset:3072
	ds_read_b128 v[90:93], v23
	ds_read_b128 v[94:97], v23 offset:1024
	s_waitcnt vmcnt(15) lgkmcnt(1)
	v_mfma_f32_16x16x32_bf16 v[0:3], v[90:93], v[0:3], 0
	ds_read_b128 v[90:93], v23 offset:2048
	s_waitcnt vmcnt(14) lgkmcnt(1)
	v_mfma_f32_16x16x32_bf16 v[0:3], v[94:97], v[30:33], v[0:3]
	ds_read_b128 v[30:33], v23 offset:3072
	s_waitcnt vmcnt(13) lgkmcnt(1)
	v_mfma_f32_16x16x32_bf16 v[0:3], v[90:93], v[34:37], v[0:3]
	ds_read_b128 v[34:37], v23 offset:4096
	s_waitcnt vmcnt(12) lgkmcnt(1)
	v_mfma_f32_16x16x32_bf16 v[0:3], v[30:33], v[38:41], v[0:3]
	ds_read_b128 v[30:33], v23 offset:5120
	s_waitcnt vmcnt(11) lgkmcnt(1)
	v_mfma_f32_16x16x32_bf16 v[0:3], v[34:37], v[42:45], v[0:3]
	ds_read_b128 v[34:37], v23 offset:6144
	s_waitcnt vmcnt(10) lgkmcnt(1)
	v_mfma_f32_16x16x32_bf16 v[0:3], v[30:33], v[46:49], v[0:3]
	ds_read_b128 v[30:33], v23 offset:7168
	s_waitcnt vmcnt(9) lgkmcnt(1)
	v_mfma_f32_16x16x32_bf16 v[0:3], v[34:37], v[50:53], v[0:3]
	ds_read_b128 v[34:37], v23 offset:8192
	s_waitcnt vmcnt(8) lgkmcnt(1)
	v_mfma_f32_16x16x32_bf16 v[0:3], v[30:33], v[54:57], v[0:3]
	ds_read_b128 v[30:33], v23 offset:9216
	s_waitcnt vmcnt(7) lgkmcnt(1)
	v_mfma_f32_16x16x32_bf16 v[0:3], v[34:37], v[58:61], v[0:3]
	ds_read_b128 v[34:37], v23 offset:10240
	s_waitcnt vmcnt(6) lgkmcnt(1)
	v_mfma_f32_16x16x32_bf16 v[0:3], v[30:33], v[62:65], v[0:3]
	ds_read_b128 v[30:33], v23 offset:11264
	s_waitcnt vmcnt(5) lgkmcnt(1)
	v_mfma_f32_16x16x32_bf16 v[0:3], v[34:37], v[66:69], v[0:3]
	ds_read_b128 v[34:37], v23 offset:12288
	s_waitcnt vmcnt(4) lgkmcnt(1)
	v_mfma_f32_16x16x32_bf16 v[0:3], v[30:33], v[70:73], v[0:3]
	ds_read_b128 v[30:33], v23 offset:13312
	s_waitcnt vmcnt(3) lgkmcnt(1)
	v_mfma_f32_16x16x32_bf16 v[0:3], v[34:37], v[74:77], v[0:3]
	ds_read_b128 v[34:37], v23 offset:14336
	s_waitcnt vmcnt(2) lgkmcnt(1)
	v_mfma_f32_16x16x32_bf16 v[0:3], v[30:33], v[78:81], v[0:3]
	ds_read_b128 v[30:33], v23 offset:15360
	s_waitcnt vmcnt(1) lgkmcnt(1)
; __device__ __forceinline__ void st_bf16x4(bf16_t* p, f32x4 v) { uint2 o; o.x = cvt_pk_bf16(v[0], v[1]); o.y = cvt_pk_bf16(v[2], v[3]); *(uint2*)p = o; }
;     __device__ __forceinline__ void frag(const f32x4 a, int row, int c) const { if (row < NB) *(f32x4*)(mod + (size_t)row * NMOD + c) = a + *(const f32x4*)(b_ada + c); }
;     __device__ __forceinline__ void frag(f32x4 v, int row, int c) const {
; #pragma unroll
;         for (int j = 0; j < 4; ++j) { const float r = fmaxf(v[j], 0.f); v[j] = r * r; }
;         st_bf16x4(T + (size_t)row * DFF + (c & ~31) + perm32(c & 31), v); }
; template <int KSPLIT, int BATCH, bool SHAREB = false, class Epi>
; __device__ __forceinline__ void small_gemm_w(const bf16_t* __restrict__ A, int nm16, const bf16_t* __restrict__ Bt, int N, int K, const Epi& E, int row_base, float* smem) {
;     ...
;                     for (int i = 0; i < BATCH; ++i) { Frag b; b.q = Bs[(s0 + i) * 64 + lane]; acc = __builtin_amdgcn_mfma_f32_16x16x32_bf16(b.v, a[i].v, acc, 0, 0, 0); }
;                     __builtin_amdgcn_sched_barrier(0); } }
	v_mfma_f32_16x16x32_bf16 v[0:3], v[34:37], v[82:85], v[0:3]
	s_waitcnt vmcnt(0) lgkmcnt(0)
	v_mfma_f32_16x16x32_bf16 v[0:3], v[30:33], v[86:89], v[0:3]
	s_add_u32 s76, s76, 0x1000
	s_addc_u32 s77, s77, 0
	global_load_dwordx4 v[30:33], v98, s[76:77]
	global_load_dwordx4 v[34:37], v98, s[76:77] offset:1024
	global_load_dwordx4 v[38:41], v98, s[76:77] offset:2048
	global_load_dwordx4 v[42:45], v98, s[76:77] offset:3072
	s_add_u32 s76, s76, 0x1000
	s_addc_u32 s77, s77, 0
	global_load_dwordx4 v[46:49], v98, s[76:77]
	global_load_dwordx4 v[50:53], v98, s[76:77] offset:1024
	global_load_dwordx4 v[54:57], v98, s[76:77] offset:2048
	global_load_dwordx4 v[58:61], v98, s[76:77] offset:3072
	s_add_u32 s76, s76, 0x1000
	s_addc_u32 s77, s77, 0
	global_load_dwordx4 v[62:65], v98, s[76:77]
	global_load_dwordx4 v[66:69], v98, s[76:77] offset:1024
	global_load_dwordx4 v[70:73], v98, s[76:77] offset:2048
	global_load_dwordx4 v[74:77], v98, s[76:77] offset:3072
	s_add_u32 s76, s76, 0x1000
	s_addc_u32 s77, s77, 0
	global_load_dwordx4 v[78:81], v98, s[76:77]
	global_load_dwordx4 v[82:85], v98, s[76:77] offset:1024
	global_load_dwordx4 v[86:89], v98, s[76:77] offset:2048
	global_load_dwordx4 v[90:93], v98, s[76:77] offset:3072
	ds_read_b128 v[94:97], v23 offset:16384
	ds_read_b128 v[98:101], v23 offset:17408
	s_waitcnt vmcnt(15) lgkmcnt(1)
	v_mfma_f32_16x16x32_bf16 v[0:3], v[94:97], v[30:33], v[0:3]
	ds_read_b128 v[30:33], v23 offset:18432
	s_waitcnt vmcnt(14) lgkmcnt(1)
	v_mfma_f32_16x16x32_bf16 v[0:3], v[98:101], v[34:37], v[0:3]
	ds_read_b128 v[34:37], v23 offset:19456
	s_waitcnt vmcnt(13) lgkmcnt(1)
	v_mfma_f32_16x16x32_bf16 v[0:3], v[30:33], v[38:41], v[0:3]
	ds_read_b128 v[30:33], v23 offset:20480
	s_waitcnt vmcnt(12) lgkmcnt(1)
	v_mfma_f32_16x16x32_bf16 v[0:3], v[34:37], v[42:45], v[0:3]
	ds_read_b128 v[34:37], v23 offset:21504
	s_waitcnt vmcnt(11) lgkmcnt(1)
	v_mfma_f32_16x16x32_bf16 v[0:3], v[30:33], v[46:49], v[0:3]
	ds_read_b128 v[30:33], v23 offset:22528
	s_waitcnt vmcnt(10) lgkmcnt(1)
	v_mfma_f32_16x16x32_bf16 v[0:3], v[34:37], v[50:53], v[0:3]
	ds_read_b128 v[34:37], v23 offset:23552
	s_waitcnt vmcnt(9) lgkmcnt(1)
	v_mfma_f32_16x16x32_bf16 v[0:3], v[30:33], v[54:57], v[0:3]
	ds_read_b128 v[30:33], v23 offset:24576
	s_waitcnt vmcnt(8) lgkmcnt(1)
	v_mfma_f32_16x16x32_bf16 v[0:3], v[34:37], v[58:61], v[0:3]
	ds_read_b128 v[34:37], v23 offset:25600
	s_waitcnt vmcnt(7) lgkmcnt(1)
	v_mfma_f32_16x16x32_bf16 v[0:3], v[30:33], v[62:65], v[0:3]
	ds_read_b128 v[30:33], v23 offset:26624
	s_waitcnt vmcnt(6) lgkmcnt(1)
	v_mfma_f32_16x16x32_bf16 v[0:3], v[34:37], v[66:69], v[0:3]
	ds_read_b128 v[34:37], v23 offset:27648
	s_waitcnt vmcnt(5) lgkmcnt(1)
	v_mfma_f32_16x16x32_bf16 v[0:3], v[30:33], v[70:73], v[0:3]
	ds_read_b128 v[30:33], v23 offset:28672
	s_waitcnt vmcnt(4) lgkmcnt(1)
	v_mfma_f32_16x16x32_bf16 v[0:3], v[34:37], v[74:77], v[0:3]
	ds_read_b128 v[34:37], v23 offset:29696
	s_waitcnt vmcnt(3) lgkmcnt(1)
	v_mfma_f32_16x16x32_bf16 v[0:3], v[30:33], v[78:81], v[0:3]
	ds_read_b128 v[30:33], v23 offset:30720
	s_waitcnt vmcnt(2) lgkmcnt(1)
	v_mfma_f32_16x16x32_bf16 v[0:3], v[34:37], v[82:85], v[0:3]
	ds_read_b128 v[34:37], v23 offset:31744
	s_waitcnt vmcnt(1) lgkmcnt(1)
	v_mfma_f32_16x16x32_bf16 v[0:3], v[30:33], v[86:89], v[0:3]
	s_waitcnt vmcnt(0) lgkmcnt(0)
	v_mfma_f32_16x16x32_bf16 v[0:3], v[34:37], v[90:93], v[0:3]
.LBB0_693:
	s_or_b64 exec, exec, s[0:1]
	s_barrier
	s_and_saveexec_b64 s[0:1], vcc
	s_cbranch_execz .LBB0_690
	s_nop 3
	v_max_f32_e32 v0, v0, v0
	v_max_f32_e32 v0, 0, v0
	v_mul_f32_e32 v30, v0, v0
	v_max_f32_e32 v0, v1, v1
	v_max_f32_e32 v0, 0, v0
	v_mul_f32_e32 v31, v0, v0
	v_max_f32_e32 v0, v2, v2
	v_ashrrev_i32_e32 v19, 3, v19
	v_max_f32_e32 v0, 0, v0
	v_lshlrev_b32_e32 v29, 4, v19
	v_mul_f32_e32 v32, v0, v0
	v_max_f32_e32 v0, v3, v3
	v_max_f32_e32 v0, 0, v0
	v_mul_f32_e32 v33, v0, v0
	v_lshlrev_b32_e32 v0, 17, v4
	v_add_u32_e32 v0, 0x7fffff0, v0
	v_add_u32_e32 v0, v0, v23
	v_lshrrev_b32_e32 v1, 1, v19
	v_lshl_add_u32 v0, v1, 10, v0
	v_and_b32_e32 v1, 1, v19
	v_lshl_add_u32 v0, v1, 3, v0
	v_cvt_pk_bf16_f32 v2, v30, v31
	v_cvt_pk_bf16_f32 v3, v32, v33
	global_store_dwordx2 v0, v[2:3], s[30:31]
	s_branch .LBB0_690

; template <int KSPLIT, int BATCH, bool SHAREB = false, class Epi>
; __device__ __forceinline__ void small_gemm_w(const bf16_t* __restrict__ A, int nm16, const bf16_t* __restrict__ Bt, int N, int K, const Epi& E, int row_base, float* smem) {
;     ...
;             const bf16_t* ap = A + (size_t)(m16 * 16 + fr) * K + ks * kw + fq * 8;
;             const bf16_t* bp = Bt + (size_t)(n16 * 16 + fr) * K + ks * kw + fq * 8;
;             for (int s0 = 0; s0 < kw / 32; s0 += BATCH) { Frag a[BATCH], b[BATCH];
; #pragma unroll
;                 for (int i = 0; i < BATCH; ++i) { a[i].q = *(const uint4*)(ap + (s0 + i) * 32); b[i].q = *(const uint4*)(bp + (s0 + i) * 32); }
;                 __builtin_amdgcn_sched_barrier(0);
; #pragma unroll
;                 for (int i = 0; i < BATCH; ++i) acc = __builtin_amdgcn_mfma_f32_16x16x32_bf16(b[i].v, a[i].v, acc, 0, 0, 0);
.LBB0_750:
	v_add_u32_e32 v1, s13, v7
	v_ashrrev_i32_e32 v2, 31, v1
	v_lshrrev_b32_e32 v3, 30, v2
	v_add_u32_e32 v3, v1, v3
	v_ashrrev_i32_e32 v4, 2, v3
	v_and_b32_e32 v3, -4, v3
	v_sub_u32_e32 v15, v1, v3
	v_lshrrev_b32_e32 v3, 29, v4
	v_add_u32_e32 v3, v4, v3
	v_and_b32_e32 v3, -8, v3
	v_lshrrev_b32_e32 v2, 27, v2
	v_cmp_gt_i32_e32 vcc, s3, v1
	v_sub_u32_e32 v14, v4, v3
	v_add_u32_e32 v1, v1, v2
	v_mov_b32_e32 v2, v0
	v_mov_b32_e32 v3, v0
	v_ashrrev_i32_e32 v13, 5, v1
	v_mov_b32_e32 v1, v0
	v_mov_b64_e32 v[4:5], v[2:3]
	v_mov_b64_e32 v[2:3], v[0:1]
	s_and_saveexec_b64 s[0:1], vcc
	s_cbranch_execz .LBB0_752
	v_lshlrev_b32_e32 v4, 10, v15
	v_ashrrev_i32_e32 v5, 31, v4
	v_lshlrev_b64 v[4:5], 1, v[4:5]
	v_mov_b32_e32 v9, v0
	v_and_b32_e32 v140, 63, v224
	v_lshlrev_b32_e32 v140, 4, v140
	v_lshl_add_u32 v140, v14, 17, v140
	v_lshl_add_u32 v140, v15, 15, v140
	s_mov_b64 s[76:77], s[4:5]
	v_lshl_or_b32 v2, v13, 4, v10
	v_ashrrev_i32_e32 v3, 31, v2
	v_lshlrev_b64 v[2:3], 13, v[2:3]
	v_lshl_add_u64 v[2:3], s[40:41], 0, v[2:3]
	v_lshl_add_u64 v[2:3], v[2:3], 0, v[4:5]
	v_lshl_add_u64 v[142:143], v[2:3], 0, v[8:9]
	global_load_dwordx4 v[2:5], v140, s[76:77]
	global_load_dwordx4 v[16:19], v140, s[76:77] offset:1024
	global_load_dwordx4 v[20:23], v[142:143], off
	global_load_dwordx4 v[24:27], v[142:143], off offset:64
	global_load_dwordx4 v[28:31], v140, s[76:77] offset:2048
	global_load_dwordx4 v[32:35], v140, s[76:77] offset:3072
	global_load_dwordx4 v[36:39], v[142:143], off offset:128
	global_load_dwordx4 v[40:43], v[142:143], off offset:192
	s_add_u32 s76, s76, 0x1000
	s_addc_u32 s77, s77, 0
	global_load_dwordx4 v[44:47], v140, s[76:77]
	global_load_dwordx4 v[48:51], v140, s[76:77] offset:1024
	global_load_dwordx4 v[52:55], v[142:143], off offset:256
	global_load_dwordx4 v[56:59], v[142:143], off offset:320
	global_load_dwordx4 v[60:63], v140, s[76:77] offset:2048
	global_load_dwordx4 v[64:67], v140, s[76:77] offset:3072
	global_load_dwordx4 v[68:71], v[142:143], off offset:384
	global_load_dwordx4 v[72:75], v[142:143], off offset:448
	s_add_u32 s76, s76, 0x1000
	s_addc_u32 s77, s77, 0
	global_load_dwordx4 v[76:79], v140, s[76:77]
	global_load_dwordx4 v[80:83], v140, s[76:77] offset:1024
	global_load_dwordx4 v[84:87], v[142:143], off offset:512
	global_load_dwordx4 v[88:91], v[142:143], off offset:576
	global_load_dwordx4 v[92:95], v140, s[76:77] offset:2048
	global_load_dwordx4 v[96:99], v140, s[76:77] offset:3072
	global_load_dwordx4 v[100:103], v[142:143], off offset:640
	global_load_dwordx4 v[104:107], v[142:143], off offset:704
	s_add_u32 s76, s76, 0x1000
	s_addc_u32 s77, s77, 0
	global_load_dwordx4 v[108:111], v140, s[76:77]
	global_load_dwordx4 v[112:115], v140, s[76:77] offset:1024
	global_load_dwordx4 v[116:119], v[142:143], off offset:768
	global_load_dwordx4 v[120:123], v[142:143], off offset:832
	global_load_dwordx4 v[124:127], v140, s[76:77] offset:2048
	global_load_dwordx4 v[128:131], v140, s[76:77] offset:3072
	global_load_dwordx4 v[132:135], v[142:143], off offset:896
	global_load_dwordx4 v[136:139], v[142:143], off offset:960
	s_waitcnt vmcnt(29)
	v_mfma_f32_16x16x32_bf16 v[2:5], v[20:23], v[2:5], 0
	s_waitcnt vmcnt(28)
	v_mfma_f32_16x16x32_bf16 v[2:5], v[24:27], v[16:19], v[2:5]
	s_waitcnt vmcnt(25)
	v_mfma_f32_16x16x32_bf16 v[2:5], v[36:39], v[28:31], v[2:5]
	s_waitcnt vmcnt(24)
	v_mfma_f32_16x16x32_bf16 v[2:5], v[40:43], v[32:35], v[2:5]
	s_waitcnt vmcnt(21)
	v_mfma_f32_16x16x32_bf16 v[2:5], v[52:55], v[44:47], v[2:5]
	s_waitcnt vmcnt(20)
	v_mfma_f32_16x16x32_bf16 v[2:5], v[56:59], v[48:51], v[2:5]
	s_waitcnt vmcnt(17)
	v_mfma_f32_16x16x32_bf16 v[2:5], v[68:71], v[60:63], v[2:5]
	s_waitcnt vmcnt(16)
	v_mfma_f32_16x16x32_bf16 v[2:5], v[72:75], v[64:67], v[2:5]
	s_waitcnt vmcnt(13)
	v_mfma_f32_16x16x32_bf16 v[2:5], v[84:87], v[76:79], v[2:5]
	s_waitcnt vmcnt(12)
	v_mfma_f32_16x16x32_bf16 v[2:5], v[88:91], v[80:83], v[2:5]
	s_waitcnt vmcnt(9)
; template <int KSPLIT, int BATCH, bool SHAREB = false, class Epi>
; __device__ __forceinline__ void small_gemm_w(const bf16_t* __restrict__ A, int nm16, const bf16_t* __restrict__ Bt, int N, int K, const Epi& E, int row_base, float* smem) {
;     ...
;             for (int s0 = 0; s0 < kw / 32; s0 += BATCH) { Frag a[BATCH], b[BATCH];
; #pragma unroll
;                 for (int i = 0; i < BATCH; ++i) { a[i].q = *(const uint4*)(ap + (s0 + i) * 32); b[i].q = *(const uint4*)(bp + (s0 + i) * 32); }
;                 __builtin_amdgcn_sched_barrier(0);
; #pragma unroll
;                 for (int i = 0; i < BATCH; ++i) acc = __builtin_amdgcn_mfma_f32_16x16x32_bf16(b[i].v, a[i].v, acc, 0, 0, 0);
;                 __builtin_amdgcn_sched_barrier(0); }
	v_mfma_f32_16x16x32_bf16 v[2:5], v[100:103], v[92:95], v[2:5]
	s_waitcnt vmcnt(8)
	v_mfma_f32_16x16x32_bf16 v[2:5], v[104:107], v[96:99], v[2:5]
	s_waitcnt vmcnt(5)
	v_mfma_f32_16x16x32_bf16 v[2:5], v[116:119], v[108:111], v[2:5]
	s_waitcnt vmcnt(4)
	v_mfma_f32_16x16x32_bf16 v[2:5], v[120:123], v[112:115], v[2:5]
	s_waitcnt vmcnt(1)
	v_mfma_f32_16x16x32_bf16 v[2:5], v[132:135], v[124:127], v[2:5]
	s_waitcnt vmcnt(0)
	v_mfma_f32_16x16x32_bf16 v[2:5], v[136:139], v[128:131], v[2:5]
	s_add_u32 s76, s76, 0x1000
	s_addc_u32 s77, s77, 0
	global_load_dwordx4 v[16:19], v140, s[76:77]
	global_load_dwordx4 v[20:23], v140, s[76:77] offset:1024
	global_load_dwordx4 v[24:27], v[142:143], off offset:1024
	global_load_dwordx4 v[28:31], v[142:143], off offset:1088
	global_load_dwordx4 v[32:35], v140, s[76:77] offset:2048
	global_load_dwordx4 v[36:39], v140, s[76:77] offset:3072
	global_load_dwordx4 v[40:43], v[142:143], off offset:1152
	global_load_dwordx4 v[44:47], v[142:143], off offset:1216
	s_add_u32 s76, s76, 0x1000
	s_addc_u32 s77, s77, 0
	global_load_dwordx4 v[48:51], v140, s[76:77]
	global_load_dwordx4 v[52:55], v140, s[76:77] offset:1024
	global_load_dwordx4 v[56:59], v[142:143], off offset:1280
	global_load_dwordx4 v[60:63], v[142:143], off offset:1344
	global_load_dwordx4 v[64:67], v140, s[76:77] offset:2048
	global_load_dwordx4 v[68:71], v140, s[76:77] offset:3072
	global_load_dwordx4 v[72:75], v[142:143], off offset:1408
	global_load_dwordx4 v[76:79], v[142:143], off offset:1472
	s_add_u32 s76, s76, 0x1000
	s_addc_u32 s77, s77, 0
	global_load_dwordx4 v[80:83], v140, s[76:77]
	global_load_dwordx4 v[84:87], v140, s[76:77] offset:1024
	global_load_dwordx4 v[88:91], v[142:143], off offset:1536
	global_load_dwordx4 v[92:95], v[142:143], off offset:1600
	global_load_dwordx4 v[96:99], v140, s[76:77] offset:2048
	global_load_dwordx4 v[100:103], v140, s[76:77] offset:3072
	global_load_dwordx4 v[104:107], v[142:143], off offset:1664
	global_load_dwordx4 v[108:111], v[142:143], off offset:1728
	s_add_u32 s76, s76, 0x1000
	s_addc_u32 s77, s77, 0
	global_load_dwordx4 v[112:115], v140, s[76:77]
	global_load_dwordx4 v[116:119], v140, s[76:77] offset:1024
	global_load_dwordx4 v[120:123], v[142:143], off offset:1792
	global_load_dwordx4 v[124:127], v[142:143], off offset:1856
	global_load_dwordx4 v[128:131], v140, s[76:77] offset:2048
	global_load_dwordx4 v[132:135], v140, s[76:77] offset:3072
	global_load_dwordx4 v[136:139], v[142:143], off offset:1920
	s_nop 0
	global_load_dwordx4 v[140:143], v[142:143], off offset:1984
	s_waitcnt vmcnt(29)
	v_mfma_f32_16x16x32_bf16 v[2:5], v[24:27], v[16:19], v[2:5]
	s_waitcnt vmcnt(28)
	v_mfma_f32_16x16x32_bf16 v[2:5], v[28:31], v[20:23], v[2:5]
	s_waitcnt vmcnt(25)
	v_mfma_f32_16x16x32_bf16 v[2:5], v[40:43], v[32:35], v[2:5]
	s_waitcnt vmcnt(24)
	v_mfma_f32_16x16x32_bf16 v[2:5], v[44:47], v[36:39], v[2:5]
	s_waitcnt vmcnt(21)
	v_mfma_f32_16x16x32_bf16 v[2:5], v[56:59], v[48:51], v[2:5]
	s_waitcnt vmcnt(20)
	v_mfma_f32_16x16x32_bf16 v[2:5], v[60:63], v[52:55], v[2:5]
	s_waitcnt vmcnt(17)
	v_mfma_f32_16x16x32_bf16 v[2:5], v[72:75], v[64:67], v[2:5]
	s_waitcnt vmcnt(16)
	v_mfma_f32_16x16x32_bf16 v[2:5], v[76:79], v[68:71], v[2:5]
	s_waitcnt vmcnt(13)
	v_mfma_f32_16x16x32_bf16 v[2:5], v[88:91], v[80:83], v[2:5]
	s_waitcnt vmcnt(12)
	v_mfma_f32_16x16x32_bf16 v[2:5], v[92:95], v[84:87], v[2:5]
	s_waitcnt vmcnt(9)
	v_mfma_f32_16x16x32_bf16 v[2:5], v[104:107], v[96:99], v[2:5]
	s_waitcnt vmcnt(8)
	v_mfma_f32_16x16x32_bf16 v[2:5], v[108:111], v[100:103], v[2:5]
	s_waitcnt vmcnt(5)
	v_mfma_f32_16x16x32_bf16 v[2:5], v[120:123], v[112:115], v[2:5]
	s_waitcnt vmcnt(4)
	v_mfma_f32_16x16x32_bf16 v[2:5], v[124:127], v[116:119], v[2:5]
	s_waitcnt vmcnt(1)
	v_mfma_f32_16x16x32_bf16 v[2:5], v[136:139], v[128:131], v[2:5]
	s_waitcnt vmcnt(0)
	v_mfma_f32_16x16x32_bf16 v[2:5], v[140:143], v[132:135], v[2:5]
